# next-tile index arithmetic of the gate-up tile loop moved out of the tile header into load segments 2-4 of the peeled first K iteration (dead time before LDS waits)
# speedup vs baseline: 1.0165x; 1.0165x over previous
; #define PG8_STAGE(bufoff, gbase, voff) do { _Pragma("unroll") for (int _i = 0; _i < 2; ++_i) { \
;         const unsigned _m0 = ldsb + (unsigned)((bufoff) + _i * 8192); const char* _gb = (const char*)(gbase); \
;         asm volatile("s_mov_b32 m0, %0\n\ts_nop 0\n\tglobal_load_lds_dwordx4 %1, %2" :: "s"(_m0), "v"((voff)[_i]), "s"(_gb) : "m0", "memory"); } } while (0)
; #define PG8_WAIT_V(n) asm volatile("s_waitcnt vmcnt(" #n ")" ::: "memory")
; #define PG8_WAIT_L(n) asm volatile("s_waitcnt lgkmcnt(" #n ")" ::: "memory")
; #define PG8_BAR __builtin_amdgcn_s_barrier()
;     __device__ bool next(int i, Unit& u) const {
;         const long L = (long)i * G + c; if (L >= nwg) return false;
;         int wgid = (int)L; { const int q = nwg / NXCD, r = nwg % NXCD, xcd = wgid % NXCD, off = wgid / NXCD; wgid = (xcd < r ? xcd * (q + 1) : r * (q + 1) + (xcd - r) * q) + off; }
;         const int nig = WGM * nN, gid = wgid / nig, fm = gid * WGM, gsz = (nM - fm) < WGM ? (nM - fm) : WGM;
;         u.pm = fm + ((wgid % nig) % gsz); u.pn = (wgid % nig) / gsz; return true;
; template <class Epi, bool ALIGN_EPI>
; __device__ __forceinline__ void gemm_phase(LAS unsigned char* lds, const Gemm g, const StaticOrder& S, const Epi& E) {
;     ...
;         const bool has_next = S.next(ui + 1, nxt);
;         const char* nA = has_next ? (const char*)g.A + (size_t)nxt.pm * tstepA + (size_t)nxt.pn * g.a_pn_off * 2 + (size_t)(nxt.pm >> 4) * g.a_adj : cA; const char* nB = has_next ? (const char*)g.Bt + (size_t)nxt.pn * tstepB : cB;
;         for (int t = 0; t < nt; t += 2) {
;             const bool last = (t == nt - 2);
;             const char* a1 = cA + (size_t)(t + 1) * kstep;
;             const char* a2 = last ? nA : cA + (size_t)(t + 2) * kstep; const char* b2 = last ? nB : cB + (size_t)(t + 2) * kstep;
;             const char* a3 = a2 + kstep; const char* b3 = b2 + kstep;
;             PG8_LDB(B0, 0, 0); PG8_LDB(B1, 0, 1); PG8_SCHED; PG8_LDA(At, 0, 0); PG8_STAGE(PG8_SA(1, 1), a1 + hstepA, voffA);
;             PG8_WAIT_V(8); PG8_WAIT_L(0); PG8_BAR; PG8_MMA(0, 0, At, B0); PG8_MMA(0, 1, At, B1); PG8_BAR; PG8_SCHED;
;             PG8_LDA(At, 0, 1); PG8_STAGE(PG8_SB(0, 0), b2, voffB); PG8_STAGE(PG8_SB(0, 1), b2 + hstepB, voffB); PG8_STAGE(PG8_SA(0, 0), a2, voffA);
;             PG8_WAIT_V(8); PG8_WAIT_L(0); PG8_BAR; PG8_MMA(1, 0, At, B0); PG8_MMA(1, 1, At, B1); PG8_BAR; PG8_SCHED;
.LBB0_305:
	s_add_u32 s41, s56, 0x100
	s_addc_u32 s49, s57, 0
	s_add_u32 s92, s58, 0x40080
	s_addc_u32 s93, s59, 0
	s_mov_b32 s50, -2
	s_add_u32 s30, s92, 0xfffc0080
	s_addc_u32 s31, s93, -1
	s_cmp_eq_u32 s50, 12
	s_cselect_b32 s60, s5, s30
	s_cselect_b32 s61, s4, s31
	s_cselect_b32 s58, s37, s41
	s_cselect_b32 s59, s35, s49
	s_add_u32 s56, s60, 0x80
	s_addc_u32 s57, s61, 0
	s_mov_b32 m0, s67
	s_nop 0
	global_load_lds_dwordx4 v0, s[92:93]
	s_nop 0
	s_mov_b32 m0, s65
	s_nop 0
	global_load_lds_dwordx4 v181, s[92:93]
	s_waitcnt vmcnt(8)
	s_waitcnt lgkmcnt(0)
	s_barrier
	s_setprio 1
	s_waitcnt lgkmcnt(0)
	v_mfma_f32_16x16x32_bf16 v[142:145], v[74:77], v[162:165], 0
	v_mfma_f32_16x16x32_bf16 v[142:145], v[94:97], v[166:169], v[142:145]
	v_mfma_f32_16x16x32_bf16 v[138:141], v[114:117], v[162:165], 0
	v_mfma_f32_16x16x32_bf16 v[138:141], v[134:137], v[166:169], v[138:141]
	v_mfma_f32_16x16x32_bf16 v[130:133], v[146:149], v[162:165], 0
	v_mfma_f32_16x16x32_bf16 v[130:133], v[150:153], v[166:169], v[130:133]
	v_mfma_f32_16x16x32_bf16 v[126:129], v[154:157], v[162:165], 0
	v_mfma_f32_16x16x32_bf16 v[126:129], v[158:161], v[166:169], v[126:129]
	v_mfma_f32_16x16x32_bf16 v[106:109], v[154:157], v[170:173], 0
	v_mfma_f32_16x16x32_bf16 v[106:109], v[158:161], v[174:177], v[106:109]
	v_mfma_f32_16x16x32_bf16 v[110:113], v[146:149], v[170:173], 0
	v_mfma_f32_16x16x32_bf16 v[110:113], v[150:153], v[174:177], v[110:113]
	v_mfma_f32_16x16x32_bf16 v[118:121], v[114:117], v[170:173], 0
	v_mfma_f32_16x16x32_bf16 v[118:121], v[134:137], v[174:177], v[118:121]
	v_mfma_f32_16x16x32_bf16 v[122:125], v[74:77], v[170:173], 0
	v_mfma_f32_16x16x32_bf16 v[122:125], v[94:97], v[174:177], v[122:125]
	v_mfma_f32_16x16x32_bf16 v[102:105], v[74:77], v[188:191], 0
	v_mfma_f32_16x16x32_bf16 v[102:105], v[94:97], v[202:205], v[102:105]
	v_mfma_f32_16x16x32_bf16 v[98:101], v[114:117], v[188:191], 0
	v_mfma_f32_16x16x32_bf16 v[98:101], v[134:137], v[202:205], v[98:101]
	v_mfma_f32_16x16x32_bf16 v[90:93], v[146:149], v[188:191], 0
	v_mfma_f32_16x16x32_bf16 v[90:93], v[150:153], v[202:205], v[90:93]
	v_mfma_f32_16x16x32_bf16 v[86:89], v[154:157], v[188:191], 0
	v_mfma_f32_16x16x32_bf16 v[86:89], v[158:161], v[202:205], v[86:89]
	v_mfma_f32_16x16x32_bf16 v[66:69], v[154:157], v[206:209], 0
	v_mfma_f32_16x16x32_bf16 v[66:69], v[158:161], v[210:213], v[66:69]
	v_mfma_f32_16x16x32_bf16 v[70:73], v[146:149], v[206:209], 0
	v_mfma_f32_16x16x32_bf16 v[70:73], v[150:153], v[210:213], v[70:73]
	v_mfma_f32_16x16x32_bf16 v[78:81], v[114:117], v[206:209], 0
	v_mfma_f32_16x16x32_bf16 v[78:81], v[134:137], v[210:213], v[78:81]
	v_mfma_f32_16x16x32_bf16 v[82:85], v[74:77], v[206:209], 0
	v_mfma_f32_16x16x32_bf16 v[82:85], v[94:97], v[210:213], v[82:85]
	s_setprio 0
	s_barrier
	ds_read_b128 v[162:165], v186 offset:16384
	ds_read_b128 v[166:169], v186 offset:17408
	ds_read_b128 v[170:173], v186 offset:18432
	ds_read_b128 v[174:177], v186 offset:19456
	ds_read_b128 v[188:191], v186 offset:20480
	ds_read_b128 v[202:205], v186 offset:21504
	ds_read_b128 v[206:209], v186 offset:22528
	ds_read_b128 v[210:213], v186 offset:23552
	s_mov_b32 m0, s29
	s_nop 0
	global_load_lds_dwordx4 v180, s[58:59]
	s_add_u32 s30, s58, 0x40000
	s_mov_b32 m0, s42
	s_nop 0
	global_load_lds_dwordx4 v182, s[58:59]
	s_addc_u32 s31, s59, 0
	s_mov_b32 m0, s43
	s_nop 0
	global_load_lds_dwordx4 v180, s[30:31]
	s_nop 0
	s_mov_b32 m0, s44
	s_nop 0
	global_load_lds_dwordx4 v182, s[30:31]
	s_nop 0
	s_mov_b32 m0, s15
	s_nop 0
	global_load_lds_dwordx4 v0, s[60:61]
	s_nop 0
	s_mov_b32 m0, s45
	s_nop 0
	global_load_lds_dwordx4 v181, s[60:61]
	s_mul_i32 s4, s85, s27
	s_mul_hi_u32 s5, s85, s87
	s_add_i32 s5, s5, s4
	s_mul_i32 s4, s85, s87
	s_add_u32 s4, s4, s16
	s_addc_u32 s5, s5, s68
	v_mov_b64_e32 v[192:193], s[46:47]
	v_cmp_lt_i64_e64 s[8:9], s[4:5], v[192:193]
	s_ashr_i32 s5, s4, 31
	s_lshr_b32 s5, s5, 29
	s_add_i32 s5, s4, s5
	s_ashr_i32 s90, s5, 3
	s_and_b32 s5, s5, -8
	s_sub_i32 s4, s4, s5
	s_lshr_b32 s5, s4, 31
	s_or_b32 s5, s78, s5
	s_mul_i32 s4, s5, s4
	s_add_i32 s4, s4, s90
	s_abs_i32 s90, s4
	v_readlane_b32 s91, v254, 48
	s_mul_hi_u32 s91, s90, s91
	s_mul_i32 s34, s91, s26
	s_sub_i32 s90, s90, s34
	s_ashr_i32 s5, s4, 31
	s_add_i32 s34, s91, 1
	s_sub_i32 s35, s90, s26
	s_cmp_ge_u32 s90, s26
	s_cselect_b32 s91, s34, s91
	s_cselect_b32 s90, s35, s90
	s_waitcnt vmcnt(8)
	s_waitcnt lgkmcnt(0)
	s_barrier
	s_setprio 1
	s_waitcnt lgkmcnt(0)
	v_mfma_f32_16x16x32_bf16 v[62:65], v[74:77], v[162:165], 0
	v_mfma_f32_16x16x32_bf16 v[62:65], v[94:97], v[166:169], v[62:65]
	v_mfma_f32_16x16x32_bf16 v[58:61], v[114:117], v[162:165], 0
	v_mfma_f32_16x16x32_bf16 v[58:61], v[134:137], v[166:169], v[58:61]
	v_mfma_f32_16x16x32_bf16 v[54:57], v[146:149], v[162:165], 0
	v_mfma_f32_16x16x32_bf16 v[54:57], v[150:153], v[166:169], v[54:57]
	v_mfma_f32_16x16x32_bf16 v[50:53], v[154:157], v[162:165], 0
	v_mfma_f32_16x16x32_bf16 v[50:53], v[158:161], v[166:169], v[50:53]
	v_mfma_f32_16x16x32_bf16 v[34:37], v[154:157], v[170:173], 0
	v_mfma_f32_16x16x32_bf16 v[34:37], v[158:161], v[174:177], v[34:37]
	v_mfma_f32_16x16x32_bf16 v[38:41], v[146:149], v[170:173], 0
	v_mfma_f32_16x16x32_bf16 v[38:41], v[150:153], v[174:177], v[38:41]
	v_mfma_f32_16x16x32_bf16 v[42:45], v[114:117], v[170:173], 0
	v_mfma_f32_16x16x32_bf16 v[42:45], v[134:137], v[174:177], v[42:45]
	v_mfma_f32_16x16x32_bf16 v[46:49], v[74:77], v[170:173], 0
	v_mfma_f32_16x16x32_bf16 v[46:49], v[94:97], v[174:177], v[46:49]
	v_mfma_f32_16x16x32_bf16 v[30:33], v[74:77], v[188:191], 0
	v_mfma_f32_16x16x32_bf16 v[30:33], v[94:97], v[202:205], v[30:33]
	v_mfma_f32_16x16x32_bf16 v[26:29], v[114:117], v[188:191], 0
	v_mfma_f32_16x16x32_bf16 v[26:29], v[134:137], v[202:205], v[26:29]
	v_mfma_f32_16x16x32_bf16 v[22:25], v[146:149], v[188:191], 0
	v_mfma_f32_16x16x32_bf16 v[22:25], v[150:153], v[202:205], v[22:25]
	v_mfma_f32_16x16x32_bf16 v[18:21], v[154:157], v[188:191], 0
	v_mfma_f32_16x16x32_bf16 v[18:21], v[158:161], v[202:205], v[18:21]
	v_mfma_f32_16x16x32_bf16 v[2:5], v[154:157], v[206:209], 0
	v_mfma_f32_16x16x32_bf16 v[2:5], v[158:161], v[210:213], v[2:5]
	v_mfma_f32_16x16x32_bf16 v[6:9], v[146:149], v[206:209], 0
	v_mfma_f32_16x16x32_bf16 v[6:9], v[150:153], v[210:213], v[6:9]
	v_mfma_f32_16x16x32_bf16 v[10:13], v[114:117], v[206:209], 0
	v_mfma_f32_16x16x32_bf16 v[10:13], v[134:137], v[210:213], v[10:13]
	v_mfma_f32_16x16x32_bf16 v[14:17], v[74:77], v[206:209], 0
	v_mfma_f32_16x16x32_bf16 v[14:17], v[94:97], v[210:213], v[14:17]
	s_setprio 0
	s_barrier
; #define PG8_STAGE(bufoff, gbase, voff) do { _Pragma("unroll") for (int _i = 0; _i < 2; ++_i) { \
;         const unsigned _m0 = ldsb + (unsigned)((bufoff) + _i * 8192); const char* _gb = (const char*)(gbase); \
;         asm volatile("s_mov_b32 m0, %0\n\ts_nop 0\n\tglobal_load_lds_dwordx4 %1, %2" :: "s"(_m0), "v"((voff)[_i]), "s"(_gb) : "m0", "memory"); } } while (0)
; #define PG8_LDA(dst, b, h) do { _Pragma("unroll") for (int m = 0; m < 4; ++m) _Pragma("unroll") for (int k = 0; k < 2; ++k) dst[m][k] = *(const LAS bf16x8*)(lds + PG8_SA(b, h) + aoff + m * 2048 + k * 1024); } while (0)
; #define PG8_LDB(dst, b, h) do { _Pragma("unroll") for (int n = 0; n < 2; ++n) _Pragma("unroll") for (int k = 0; k < 2; ++k) dst[n][k] = *(const LAS bf16x8*)(lds + PG8_SB(b, h) + boff + n * 2048 + k * 1024); } while (0)
; #define PG8_MMA(ai, bj, At, Bt) do { __builtin_amdgcn_s_setprio(1); _Pragma("unroll") for (int m = 0; m < 4; ++m) _Pragma("unroll") for (int n = 0; n < 2; ++n) _Pragma("unroll") for (int k = 0; k < 2; ++k) \
;         acc[ai][bj][m][n] = __builtin_amdgcn_mfma_f32_16x16x32_bf16(Bt[n][k], At[m][k], acc[ai][bj][m][n], 0, 0, 0); __builtin_amdgcn_s_setprio(0); } while (0)
; #define PG8_WAIT_V(n) asm volatile("s_waitcnt vmcnt(" #n ")" ::: "memory")
; #define PG8_WAIT_L(n) asm volatile("s_waitcnt lgkmcnt(" #n ")" ::: "memory")
; #define PG8_BAR __builtin_amdgcn_s_barrier()
; #define PG8_SCHED __builtin_amdgcn_sched_barrier(0)
;     __device__ bool next(int i, Unit& u) const {
;     ...
;         int wgid = (int)L; { const int q = nwg / NXCD, r = nwg % NXCD, xcd = wgid % NXCD, off = wgid / NXCD; wgid = (xcd < r ? xcd * (q + 1) : r * (q + 1) + (xcd - r) * q) + off; }
;         const int nig = WGM * nN, gid = wgid / nig, fm = gid * WGM, gsz = (nM - fm) < WGM ? (nM - fm) : WGM;
;         u.pm = fm + ((wgid % nig) % gsz); u.pn = (wgid % nig) / gsz; return true;
; template <class Epi, bool ALIGN_EPI>
; __device__ __forceinline__ void gemm_phase(LAS unsigned char* lds, const Gemm g, const StaticOrder& S, const Epi& E) {
;     ...
;             PG8_LDB(B0, 1, 0); PG8_LDB(B1, 1, 1); PG8_SCHED; PG8_LDA(At, 1, 0); PG8_STAGE(PG8_SA(0, 1), a2 + hstepA, voffA);
;             PG8_WAIT_V(8); PG8_WAIT_L(0); PG8_BAR; PG8_MMA(0, 0, At, B0); PG8_MMA(0, 1, At, B1); PG8_BAR; PG8_SCHED;
	v_add_u32_e32 v134, 0x18000, v185
	v_add_u32_e32 v158, 0x1c000, v185
	ds_read_b128 v[74:77], v134
	ds_read_b128 v[94:97], v134 offset:1024
	ds_read_b128 v[114:117], v134 offset:2048
	ds_read_b128 v[134:137], v134 offset:3072
	ds_read_b128 v[146:149], v158
	ds_read_b128 v[150:153], v158 offset:1024
	ds_read_b128 v[154:157], v158 offset:2048
	ds_read_b128 v[158:161], v158 offset:3072
	ds_read_b128 v[162:165], v186 offset:32768
	ds_read_b128 v[166:169], v186 offset:33792
	ds_read_b128 v[170:173], v186 offset:34816
	ds_read_b128 v[174:177], v186 offset:35840
	ds_read_b128 v[188:191], v186 offset:36864
	ds_read_b128 v[202:205], v186 offset:37888
	ds_read_b128 v[206:209], v186 offset:38912
	ds_read_b128 v[210:213], v186 offset:39936
	s_add_u32 s30, s60, 0x40000
	s_addc_u32 s31, s61, 0
	s_mov_b32 m0, s55
	s_nop 0
	global_load_lds_dwordx4 v0, s[30:31]
	s_nop 0
	s_mov_b32 m0, s88
	s_nop 0
	global_load_lds_dwordx4 v181, s[30:31]
	s_add_i32 s34, s91, 1
	s_cmp_ge_u32 s90, s26
	s_cselect_b32 s90, s34, s91
	s_xor_b32 s90, s90, s5
	s_sub_i32 s5, s90, s5
	s_lshl_b32 s90, s5, 3
	s_sub_i32 s91, 0x80, s90
	s_min_i32 s91, s91, 8
	s_abs_i32 s34, s91
	v_cvt_f32_u32_e32 v192, s34
	s_sub_i32 s36, 0, s34
	s_mul_i32 s5, s5, s26
	s_sub_i32 s4, s4, s5
	v_rcp_iflag_f32_e32 v192, v192
	s_abs_i32 s35, s4
	s_xor_b32 s5, s4, s91
	s_ashr_i32 s5, s5, 31
	v_mul_f32_e32 v192, 0x4f7ffffe, v192
	v_cvt_u32_f32_e32 v192, v192
	s_nop 0
	v_readfirstlane_b32 s37, v192
	s_mul_i32 s36, s36, s37
	s_mul_hi_u32 s36, s37, s36
	s_add_i32 s37, s37, s36
	s_mul_hi_u32 s36, s35, s37
	s_mul_i32 s37, s36, s34
	s_sub_i32 s35, s35, s37
	s_waitcnt vmcnt(8)
	s_waitcnt lgkmcnt(0)
	s_barrier
	s_setprio 1
	s_waitcnt lgkmcnt(0)
	v_mfma_f32_16x16x32_bf16 v[142:145], v[74:77], v[162:165], v[142:145]
	v_mfma_f32_16x16x32_bf16 v[142:145], v[94:97], v[166:169], v[142:145]
	v_mfma_f32_16x16x32_bf16 v[138:141], v[114:117], v[162:165], v[138:141]
	v_mfma_f32_16x16x32_bf16 v[138:141], v[134:137], v[166:169], v[138:141]
	v_mfma_f32_16x16x32_bf16 v[130:133], v[146:149], v[162:165], v[130:133]
	v_mfma_f32_16x16x32_bf16 v[130:133], v[150:153], v[166:169], v[130:133]
	v_mfma_f32_16x16x32_bf16 v[126:129], v[154:157], v[162:165], v[126:129]
	v_mfma_f32_16x16x32_bf16 v[126:129], v[158:161], v[166:169], v[126:129]
	v_mfma_f32_16x16x32_bf16 v[106:109], v[154:157], v[170:173], v[106:109]
	v_mfma_f32_16x16x32_bf16 v[106:109], v[158:161], v[174:177], v[106:109]
	v_mfma_f32_16x16x32_bf16 v[110:113], v[146:149], v[170:173], v[110:113]
	v_mfma_f32_16x16x32_bf16 v[110:113], v[150:153], v[174:177], v[110:113]
	v_mfma_f32_16x16x32_bf16 v[118:121], v[114:117], v[170:173], v[118:121]
	v_mfma_f32_16x16x32_bf16 v[118:121], v[134:137], v[174:177], v[118:121]
	v_mfma_f32_16x16x32_bf16 v[122:125], v[74:77], v[170:173], v[122:125]
	v_mfma_f32_16x16x32_bf16 v[122:125], v[94:97], v[174:177], v[122:125]
	v_mfma_f32_16x16x32_bf16 v[102:105], v[74:77], v[188:191], v[102:105]
	v_mfma_f32_16x16x32_bf16 v[102:105], v[94:97], v[202:205], v[102:105]
	v_mfma_f32_16x16x32_bf16 v[98:101], v[114:117], v[188:191], v[98:101]
	v_mfma_f32_16x16x32_bf16 v[98:101], v[134:137], v[202:205], v[98:101]
	v_mfma_f32_16x16x32_bf16 v[90:93], v[146:149], v[188:191], v[90:93]
	v_mfma_f32_16x16x32_bf16 v[90:93], v[150:153], v[202:205], v[90:93]
	v_mfma_f32_16x16x32_bf16 v[86:89], v[154:157], v[188:191], v[86:89]
	v_mfma_f32_16x16x32_bf16 v[86:89], v[158:161], v[202:205], v[86:89]
	v_mfma_f32_16x16x32_bf16 v[66:69], v[154:157], v[206:209], v[66:69]
	v_mfma_f32_16x16x32_bf16 v[66:69], v[158:161], v[210:213], v[66:69]
	v_mfma_f32_16x16x32_bf16 v[70:73], v[146:149], v[206:209], v[70:73]
	v_mfma_f32_16x16x32_bf16 v[70:73], v[150:153], v[210:213], v[70:73]
	v_mfma_f32_16x16x32_bf16 v[78:81], v[114:117], v[206:209], v[78:81]
	v_mfma_f32_16x16x32_bf16 v[78:81], v[134:137], v[210:213], v[78:81]
	v_mfma_f32_16x16x32_bf16 v[82:85], v[74:77], v[206:209], v[82:85]
	v_mfma_f32_16x16x32_bf16 v[82:85], v[94:97], v[210:213], v[82:85]
	s_setprio 0
	s_barrier
; #define PG8_STAGE(bufoff, gbase, voff) do { _Pragma("unroll") for (int _i = 0; _i < 2; ++_i) { \
;         const unsigned _m0 = ldsb + (unsigned)((bufoff) + _i * 8192); const char* _gb = (const char*)(gbase); \
;         asm volatile("s_mov_b32 m0, %0\n\ts_nop 0\n\tglobal_load_lds_dwordx4 %1, %2" :: "s"(_m0), "v"((voff)[_i]), "s"(_gb) : "m0", "memory"); } } while (0)
;     __device__ bool next(int i, Unit& u) const {
;     ...
;         const int nig = WGM * nN, gid = wgid / nig, fm = gid * WGM, gsz = (nM - fm) < WGM ? (nM - fm) : WGM;
;         u.pm = fm + ((wgid % nig) % gsz); u.pn = (wgid % nig) / gsz; return true;
; template <class Epi, bool ALIGN_EPI>
; __device__ __forceinline__ void gemm_phase(LAS unsigned char* lds, const Gemm g, const StaticOrder& S, const Epi& E) {
;     ...
;         const char* nA = has_next ? (const char*)g.A + (size_t)nxt.pm * tstepA + (size_t)nxt.pn * g.a_pn_off * 2 + (size_t)(nxt.pm >> 4) * g.a_adj : cA; const char* nB = has_next ? (const char*)g.Bt + (size_t)nxt.pn * tstepB : cB;
;         for (int t = 0; t < nt; t += 2) {
;             const bool last = (t == nt - 2);
;             const char* a1 = cA + (size_t)(t + 1) * kstep;
;             const char* a2 = last ? nA : cA + (size_t)(t + 2) * kstep; const char* b2 = last ? nB : cB + (size_t)(t + 2) * kstep;
;             const char* a3 = a2 + kstep; const char* b3 = b2 + kstep;
;             PG8_LDB(B0, 0, 0); PG8_LDB(B1, 0, 1); PG8_SCHED; PG8_LDA(At, 0, 0); PG8_STAGE(PG8_SA(1, 1), a1 + hstepA, voffA);
;             PG8_WAIT_V(8); PG8_WAIT_L(0); PG8_BAR; PG8_MMA(0, 0, At, B0); PG8_MMA(0, 1, At, B1); PG8_BAR; PG8_SCHED;
;             PG8_LDA(At, 0, 1); PG8_STAGE(PG8_SB(0, 0), b2, voffB); PG8_STAGE(PG8_SB(0, 1), b2 + hstepB, voffB); PG8_STAGE(PG8_SA(0, 0), a2, voffA);
;             PG8_WAIT_V(8); PG8_WAIT_L(0); PG8_BAR; PG8_MMA(1, 0, At, B0); PG8_MMA(1, 1, At, B1); PG8_BAR; PG8_SCHED;
;             PG8_LDB(B0, 1, 0); PG8_LDB(B1, 1, 1); PG8_SCHED; PG8_LDA(At, 1, 0); PG8_STAGE(PG8_SA(0, 1), a2 + hstepA, voffA);
;             PG8_WAIT_V(8); PG8_WAIT_L(0); PG8_BAR; PG8_MMA(0, 0, At, B0); PG8_MMA(0, 1, At, B1); PG8_BAR; PG8_SCHED;
;             PG8_LDA(At, 1, 1); PG8_STAGE(PG8_SB(1, 0), b3, voffB); PG8_STAGE(PG8_SB(1, 1), b3 + hstepB, voffB); PG8_STAGE(PG8_SA(1, 0), a3, voffA);
;             PG8_WAIT_V(8); PG8_WAIT_L(0); PG8_BAR; PG8_MMA(1, 0, At, B0); PG8_MMA(1, 1, At, B1); PG8_BAR; PG8_SCHED;
	ds_read_b128 v[162:165], v186 offset:49152
	ds_read_b128 v[166:169], v186 offset:50176
	ds_read_b128 v[170:173], v186 offset:51200
	ds_read_b128 v[174:177], v186 offset:52224
	ds_read_b128 v[188:191], v186 offset:53248
	ds_read_b128 v[202:205], v186 offset:54272
	ds_read_b128 v[206:209], v186 offset:55296
	ds_read_b128 v[210:213], v186 offset:56320
	s_add_u32 s30, s58, 0x80
	s_addc_u32 s31, s59, 0
	s_mov_b32 m0, s94
	s_nop 0
	global_load_lds_dwordx4 v180, s[30:31]
	s_nop 0
	s_mov_b32 m0, s95
	s_nop 0
	global_load_lds_dwordx4 v182, s[30:31]
	s_add_u32 s30, s58, 0x40080
	s_addc_u32 s31, s59, 0
	s_mov_b32 m0, s17
	s_nop 0
	global_load_lds_dwordx4 v180, s[30:31]
	s_nop 0
	s_mov_b32 m0, s53
	s_nop 0
	global_load_lds_dwordx4 v182, s[30:31]
	s_nop 0
	s_mov_b32 m0, s96
	s_nop 0
	global_load_lds_dwordx4 v0, s[56:57]
	s_nop 0
	s_mov_b32 m0, s97
	s_nop 0
	global_load_lds_dwordx4 v181, s[56:57]
	s_add_i32 s37, s36, 1
	s_sub_i32 s38, s35, s34
	s_cmp_ge_u32 s35, s34
	s_cselect_b32 s36, s37, s36
	s_cselect_b32 s35, s38, s35
	s_add_i32 s37, s36, 1
	s_cmp_ge_u32 s35, s34
	s_cselect_b32 s34, s37, s36
	s_xor_b32 s34, s34, s5
	s_sub_i32 s34, s34, s5
	s_mul_i32 s5, s34, s91
	s_sub_i32 s4, s4, s5
	s_add_i32 s36, s4, s90
	s_ashr_i32 s37, s36, 31
	s_lshl_b64 s[4:5], s[36:37], 19
	s_add_u32 s38, s18, s4
	s_addc_u32 s39, s19, s5
	s_and_b64 s[4:5], s[8:9], exec
	s_cselect_b32 s4, s39, s59
	s_cselect_b32 s5, s38, s58
	s_ashr_i32 s35, s34, 31
	s_lshl_b64 vcc, s[34:35], 19
	s_add_u32 s90, s1, vcc_lo
	s_addc_u32 s91, s14, vcc_hi
	s_and_b64 vcc, s[8:9], exec
	s_cselect_b32 s35, s91, s57
	s_cselect_b32 s37, s90, s56
	s_waitcnt vmcnt(8)
	s_waitcnt lgkmcnt(0)
	s_barrier
	s_setprio 1
	s_waitcnt lgkmcnt(0)
	v_mfma_f32_16x16x32_bf16 v[62:65], v[74:77], v[162:165], v[62:65]
	v_mfma_f32_16x16x32_bf16 v[62:65], v[94:97], v[166:169], v[62:65]
	v_mfma_f32_16x16x32_bf16 v[58:61], v[114:117], v[162:165], v[58:61]
	v_mfma_f32_16x16x32_bf16 v[58:61], v[134:137], v[166:169], v[58:61]
	v_mfma_f32_16x16x32_bf16 v[54:57], v[146:149], v[162:165], v[54:57]
	v_mfma_f32_16x16x32_bf16 v[54:57], v[150:153], v[166:169], v[54:57]
	v_mfma_f32_16x16x32_bf16 v[50:53], v[154:157], v[162:165], v[50:53]
	v_mfma_f32_16x16x32_bf16 v[50:53], v[158:161], v[166:169], v[50:53]
	v_mfma_f32_16x16x32_bf16 v[34:37], v[154:157], v[170:173], v[34:37]
	v_mfma_f32_16x16x32_bf16 v[34:37], v[158:161], v[174:177], v[34:37]
	v_mfma_f32_16x16x32_bf16 v[38:41], v[146:149], v[170:173], v[38:41]
	v_mfma_f32_16x16x32_bf16 v[38:41], v[150:153], v[174:177], v[38:41]
	v_mfma_f32_16x16x32_bf16 v[42:45], v[114:117], v[170:173], v[42:45]
	v_mfma_f32_16x16x32_bf16 v[42:45], v[134:137], v[174:177], v[42:45]
	v_mfma_f32_16x16x32_bf16 v[46:49], v[74:77], v[170:173], v[46:49]
	v_mfma_f32_16x16x32_bf16 v[46:49], v[94:97], v[174:177], v[46:49]
	v_mfma_f32_16x16x32_bf16 v[30:33], v[74:77], v[188:191], v[30:33]
	v_mfma_f32_16x16x32_bf16 v[30:33], v[94:97], v[202:205], v[30:33]
	v_mfma_f32_16x16x32_bf16 v[26:29], v[114:117], v[188:191], v[26:29]
	v_mfma_f32_16x16x32_bf16 v[26:29], v[134:137], v[202:205], v[26:29]
	v_mfma_f32_16x16x32_bf16 v[22:25], v[146:149], v[188:191], v[22:25]
	v_mfma_f32_16x16x32_bf16 v[22:25], v[150:153], v[202:205], v[22:25]
	v_mfma_f32_16x16x32_bf16 v[18:21], v[154:157], v[188:191], v[18:21]
	v_mfma_f32_16x16x32_bf16 v[18:21], v[158:161], v[202:205], v[18:21]
	v_mfma_f32_16x16x32_bf16 v[2:5], v[154:157], v[206:209], v[2:5]
	v_mfma_f32_16x16x32_bf16 v[2:5], v[158:161], v[210:213], v[2:5]
	v_mfma_f32_16x16x32_bf16 v[6:9], v[146:149], v[206:209], v[6:9]
	v_mfma_f32_16x16x32_bf16 v[6:9], v[150:153], v[210:213], v[6:9]
	v_mfma_f32_16x16x32_bf16 v[10:13], v[114:117], v[206:209], v[10:13]
	v_mfma_f32_16x16x32_bf16 v[10:13], v[134:137], v[210:213], v[10:13]
	v_mfma_f32_16x16x32_bf16 v[14:17], v[74:77], v[206:209], v[14:17]
	v_mfma_f32_16x16x32_bf16 v[14:17], v[94:97], v[210:213], v[14:17]
	s_setprio 0
	s_barrier
	s_add_i32 s50, s50, 2
	s_add_u32 s41, s41, 0x100
	s_addc_u32 s49, s49, 0
	s_add_u32 s92, s92, 0x100
	s_addc_u32 s93, s93, 0
	s_cmp_gt_u32 s50, 13
